# grid barrier followers: L1 invalidate issued before the polling loop instead of after the release
# speedup vs baseline: 1.0107x; 1.0002x over previous
; __device__ __forceinline__ unsigned xb_ld(unsigned* p)              { return __hip_atomic_load(p, __ATOMIC_RELAXED, __HIP_MEMORY_SCOPE_AGENT); }
; __device__ __forceinline__ unsigned xb_add(unsigned* p, unsigned v) { return __hip_atomic_fetch_add(p, v, __ATOMIC_RELAXED, __HIP_MEMORY_SCOPE_AGENT); }
; #define XB_SPIN(cond, bar) do { unsigned _sp = 0; while (cond) { __builtin_amdgcn_s_sleep(1); \
;     if ((++_sp & 255u) == 0u) { if (xb_ld(&(bar)[XB_TMO])) break; if (_sp > XB_SPIN_CAP) { atomicAdd(&(bar)[XB_TMO], 1u); break; } } } } while (0)
; __device__ __forceinline__ void xcd_barrier(unsigned* bar, volatile LAS unsigned* st, const int tid) {
;     ...
;         unsigned nloc = st[0], nx = st[1];
;         if (nloc == 0u) { xcd_barrier_complete(bar, x, nloc, nx); st[0] = nloc; st[1] = nx; }
;         const unsigned old = xb_add(&bar[XB_XSUB(x)], 1u);
;         const unsigned gen = old / nloc;
;         if (old + 1u == (gen + 1u) * nloc) {
;             __builtin_amdgcn_fence(__ATOMIC_RELEASE, "agent");
;             asm volatile("s_waitcnt vmcnt(0)" ::: "memory");
;             const unsigned og = xb_add(&bar[XB_TOP], 1u);
;             const unsigned tg = og / nx;
;             if (og + 1u == (tg + 1u) * nx) xb_add(&bar[XB_TOPGEN], 1u);
;             else XB_SPIN(xb_ld(&bar[XB_TOPGEN]) == tg, bar);
;             __builtin_amdgcn_fence(__ATOMIC_ACQUIRE, "agent");
;             xb_add(&bar[XB_XGEN(x)], 1u);
;             asm volatile("s_waitcnt vmcnt(0)" ::: "memory");
;         } else {
;             XB_SPIN(xb_ld(&bar[XB_XGEN(x)]) == gen, bar);
.LBB0_68:
	s_or_b64 exec, exec, s[24:25]
	v_cvt_f32_u32_e32 v4, v2
	s_waitcnt vmcnt(0)
	v_readfirstlane_b32 s3, v3
	v_sub_u32_e32 v3, 0, v2
	v_rcp_iflag_f32_e32 v4, v4
	v_add_u32_e32 v5, s3, v1
	v_mul_f32_e32 v4, 0x4f7ffffe, v4
	v_cvt_u32_f32_e32 v4, v4
	v_mul_lo_u32 v1, v3, v4
	v_mul_hi_u32 v1, v4, v1
	v_add_u32_e32 v1, v4, v1
	v_mul_hi_u32 v1, v5, v1
	v_mul_lo_u32 v3, v1, v2
	v_sub_u32_e32 v3, v5, v3
	v_add_u32_e32 v4, 1, v1
	v_cmp_ge_u32_e32 vcc, v3, v2
	s_nop 1
	v_cndmask_b32_e32 v1, v1, v4, vcc
	v_sub_u32_e32 v4, v3, v2
	v_cndmask_b32_e32 v3, v3, v4, vcc
	v_add_u32_e32 v4, 1, v1
	v_cmp_ge_u32_e32 vcc, v3, v2
	v_add_u32_e32 v3, 1, v5
	s_nop 0
	v_cndmask_b32_e32 v1, v1, v4, vcc
	v_mul_lo_u32 v4, v2, v1
	v_add_u32_e32 v2, v4, v2
	v_cmp_ne_u32_e32 vcc, v3, v2
	s_and_saveexec_b64 s[22:23], vcc
	s_xor_b64 s[22:23], exec, s[22:23]
	s_cbranch_execz .LBB0_82
	buffer_inv sc0
	v_mov_b32_e32 v0, 0x2000
	global_load_dword v0, v0, s[16:17] offset:1024 sc1
	s_add_u32 s40, s16, 0x2400
	s_addc_u32 s41, s17, 0
	s_waitcnt vmcnt(0)
	v_cmp_eq_u32_e32 vcc, v0, v1
	s_and_saveexec_b64 s[30:31], vcc
	s_cbranch_execz .LBB0_81
	s_mov_b32 s3, 1
	s_mov_b64 s[42:43], 0
	s_branch .LBB0_72

; __device__ __forceinline__ unsigned xb_ld(unsigned* p)              { return __hip_atomic_load(p, __ATOMIC_RELAXED, __HIP_MEMORY_SCOPE_AGENT); }
; #define XB_SPIN(cond, bar) do { unsigned _sp = 0; while (cond) { __builtin_amdgcn_s_sleep(1); \
;     if ((++_sp & 255u) == 0u) { if (xb_ld(&(bar)[XB_TMO])) break; if (_sp > XB_SPIN_CAP) { atomicAdd(&(bar)[XB_TMO], 1u); break; } } } } while (0)
; __device__ __forceinline__ void xcd_barrier(unsigned* bar, volatile LAS unsigned* st, const int tid) {
;     ...
;             XB_SPIN(xb_ld(&bar[XB_XGEN(x)]) == gen, bar);
;             __builtin_amdgcn_fence(__ATOMIC_ACQUIRE, "agent");
;             asm volatile("s_waitcnt vmcnt(0)" ::: "memory");
.LBB0_81:
	s_or_b64 exec, exec, s[30:31]
	s_waitcnt vmcnt(0) lgkmcnt(0)
	s_waitcnt vmcnt(0)
